# speedup vs baseline: 1.0298x; 1.0102x over previous
; #define SCHEDB() __builtin_amdgcn_sched_barrier(0)
; DEVI void gemm_residual(const bfr* W, const bfr* X, int K, float* out, char* shm, const float* xp = nullptr, const float* xs = nullptr) {
;   gemm8_linear(W, 8, X, 128, K, shm, [&](f32x4 (&acc)[2][2][4][2], int pa, int pb) { EPI8_COORDS;
; #pragma unroll
;     for (int ai = 0; ai < 2; ++ai)
; #pragma unroll
;       for (int bj = 0; bj < 2; ++bj) {
; #pragma unroll
;         for (int n = 0; n < 2; ++n)
; #pragma unroll
;           for (int m = 0; m < 4; m += 2) {
;             const int tk = pb * 256 + bj * 128 + e_wc * 32 + n * 16 + e_fr;
;             const int fi = pa * 256 + ai * 128 + e_wr * 64 + (m + (e_fq & 1)) * 16 + (e_fq >> 1) * 8;
;             f32x4* d = reinterpret_cast<f32x4*>(out + (long)tk * DM + fi);
;             const f32x4* sp = xp ? reinterpret_cast<const f32x4*>((tk < 16384 ? xp + (long)tk * DM : xs + (long)(tk - 16384) * DM) + fi) : d;
;             f32x4 o0 = sp[0], o1 = sp[1];
;             const f32x4 va = acc[ai][bj][m][n], vb2 = acc[ai][bj][m + 1][n];
; #pragma unroll
;             for (int e = 0; e < 4; ++e) { auto rr = __builtin_amdgcn_permlane16_swap(__float_as_uint(va[e]), __float_as_uint(vb2[e]), false, false);
;               o0[e] += __uint_as_float(rr[0]); o1[e] += __uint_as_float(rr[1]); }
;             d[0] = o0; d[1] = o1; }
;         SCHEDB(); } });
.LBB0_58:
	v_mov_b32_e32 v128, v164
	v_lshrrev_b32_e32 v130, 1, v128
	v_and_b32_e32 v129, 15, v128
	v_and_b32_e32 v130, 0x60, v130
	v_or3_b32 v130, v129, v130, s10
	v_ashrrev_i32_e32 v129, 2, v128
	v_and_b32_e32 v129, 0xffffffc0, v129
	v_lshrrev_b32_e32 v131, 2, v128
	v_and_or_b32 v128, v128, 16, s8
	v_add_u32_e32 v128, v128, v129
	v_and_or_b32 v128, v131, 8, v128
	v_ashrrev_i32_e32 v131, 31, v130
	v_readlane_b32 s8, v255, 2
	v_lshlrev_b64 v[132:133], 13, v[130:131]
	v_readlane_b32 s10, v255, 4
	v_readlane_b32 s11, v255, 5
	s_nop 1
	v_ashrrev_i32_e32 v129, 31, v128
	v_lshl_add_u64 v[134:135], s[10:11], 0, v[132:133]
	v_lshlrev_b64 v[132:133], 2, v[128:129]
	v_lshl_add_u64 v[128:129], v[134:135], 0, v[132:133]
	v_readlane_b32 s9, v255, 3
	s_nop 1
	v_or_b32_e32 v244, 16, v130
	v_ashrrev_i32_e32 v245, 31, v244
	v_lshlrev_b64 v[244:245], 13, v[244:245]
	v_lshl_add_u64 v[244:245], s[10:11], 0, v[244:245]
	v_lshl_add_u64 v[244:245], v[244:245], 0, v[132:133]
	v_or_b32_e32 v246, 0x80, v130
	v_ashrrev_i32_e32 v247, 31, v246
	v_lshlrev_b64 v[246:247], 13, v[246:247]
	v_lshl_add_u64 v[246:247], s[10:11], 0, v[246:247]
	v_lshl_add_u64 v[246:247], v[246:247], 0, v[132:133]
	v_or_b32_e32 v248, 0x90, v130
	v_ashrrev_i32_e32 v249, 31, v248
	v_lshlrev_b64 v[248:249], 13, v[248:249]
	v_lshl_add_u64 v[248:249], s[10:11], 0, v[248:249]
	v_lshl_add_u64 v[248:249], v[248:249], 0, v[132:133]
	global_load_dwordx4 v[196:199], v[128:129], off offset:16
	global_load_dwordx4 v[200:203], v[128:129], off
	global_load_dwordx4 v[204:207], v[128:129], off offset:144
	global_load_dwordx4 v[208:211], v[128:129], off offset:128
	global_load_dwordx4 v[212:215], v[244:245], off offset:16
	global_load_dwordx4 v[216:219], v[244:245], off
	global_load_dwordx4 v[220:223], v[244:245], off offset:144
	global_load_dwordx4 v[224:227], v[244:245], off offset:128
	global_load_dwordx4 v[228:231], v[246:247], off offset:16
	global_load_dwordx4 v[232:235], v[246:247], off
	global_load_dwordx4 v[236:239], v[246:247], off offset:144
	global_load_dwordx4 v[240:243], v[246:247], off offset:128
	global_load_dwordx4 v[174:177], v[248:249], off offset:16
	global_load_dwordx4 v[178:181], v[248:249], off
	global_load_dwordx4 v[182:185], v[248:249], off offset:144
	global_load_dwordx4 v[186:189], v[248:249], off offset:128
	v_permlane16_swap_b32_e32 v120, v124
	v_permlane16_swap_b32_e32 v121, v125
	v_permlane16_swap_b32_e32 v122, v126
	v_permlane16_swap_b32_e32 v123, v127
	v_permlane16_swap_b32_e32 v112, v116
	v_permlane16_swap_b32_e32 v113, v117
	v_permlane16_swap_b32_e32 v114, v118
	v_permlane16_swap_b32_e32 v115, v119
	v_permlane16_swap_b32_e32 v104, v108
	v_permlane16_swap_b32_e32 v105, v109
	v_permlane16_swap_b32_e32 v106, v110
	v_permlane16_swap_b32_e32 v107, v111
	v_permlane16_swap_b32_e32 v100, v96
	v_permlane16_swap_b32_e32 v101, v97
	v_permlane16_swap_b32_e32 v102, v98
	v_permlane16_swap_b32_e32 v103, v99
	v_permlane16_swap_b32_e32 v88, v92
	v_permlane16_swap_b32_e32 v89, v93
	v_permlane16_swap_b32_e32 v90, v94
	v_permlane16_swap_b32_e32 v91, v95
	v_permlane16_swap_b32_e32 v80, v84
	v_permlane16_swap_b32_e32 v81, v85
	v_permlane16_swap_b32_e32 v82, v86
	v_permlane16_swap_b32_e32 v83, v87
	v_permlane16_swap_b32_e32 v72, v76
	v_permlane16_swap_b32_e32 v73, v77
	v_permlane16_swap_b32_e32 v74, v78
	v_permlane16_swap_b32_e32 v75, v79
	v_permlane16_swap_b32_e32 v68, v64
	v_permlane16_swap_b32_e32 v69, v65
	v_permlane16_swap_b32_e32 v70, v66
	v_permlane16_swap_b32_e32 v71, v67
	v_permlane16_swap_b32_e32 v56, v60
	v_permlane16_swap_b32_e32 v57, v61
	v_permlane16_swap_b32_e32 v58, v62
	v_permlane16_swap_b32_e32 v59, v63
	v_permlane16_swap_b32_e32 v48, v52
	v_permlane16_swap_b32_e32 v49, v53
	v_permlane16_swap_b32_e32 v50, v54
	v_permlane16_swap_b32_e32 v51, v55
	v_permlane16_swap_b32_e32 v40, v44
	v_permlane16_swap_b32_e32 v41, v45
	v_permlane16_swap_b32_e32 v42, v46
	v_permlane16_swap_b32_e32 v43, v47
	v_permlane16_swap_b32_e32 v36, v32
	v_permlane16_swap_b32_e32 v37, v33
	v_permlane16_swap_b32_e32 v38, v34
	v_permlane16_swap_b32_e32 v39, v35
	v_permlane16_swap_b32_e32 v24, v28
	v_permlane16_swap_b32_e32 v25, v29
	v_permlane16_swap_b32_e32 v26, v30
	v_permlane16_swap_b32_e32 v27, v31
	v_permlane16_swap_b32_e32 v16, v20
	v_permlane16_swap_b32_e32 v17, v21
	v_permlane16_swap_b32_e32 v18, v22
	v_permlane16_swap_b32_e32 v19, v23
	v_permlane16_swap_b32_e32 v8, v12
	v_permlane16_swap_b32_e32 v9, v13
	v_permlane16_swap_b32_e32 v10, v14
	v_permlane16_swap_b32_e32 v11, v15
	v_permlane16_swap_b32_e32 v4, v0
	v_permlane16_swap_b32_e32 v5, v1
	v_permlane16_swap_b32_e32 v6, v2
	v_permlane16_swap_b32_e32 v7, v3
	s_waitcnt vmcnt(14)
	v_pk_add_f32 v[126:127], v[198:199], v[126:127]
	v_pk_add_f32 v[122:123], v[202:203], v[122:123]
	v_pk_add_f32 v[120:121], v[200:201], v[120:121]
	v_pk_add_f32 v[124:125], v[196:197], v[124:125]
	global_store_dwordx4 v[128:129], v[120:123], off
	global_store_dwordx4 v[128:129], v[124:127], off offset:16
	global_load_dwordx4 v[196:199], v[128:129], off offset:528
	global_load_dwordx4 v[200:203], v[128:129], off offset:512
	s_waitcnt vmcnt(16)
	v_pk_add_f32 v[118:119], v[206:207], v[118:119]
	v_pk_add_f32 v[114:115], v[210:211], v[114:115]
	v_pk_add_f32 v[112:113], v[208:209], v[112:113]
	v_pk_add_f32 v[116:117], v[204:205], v[116:117]
	global_store_dwordx4 v[128:129], v[112:115], off offset:128
	global_store_dwordx4 v[128:129], v[116:119], off offset:144
	global_load_dwordx4 v[204:207], v[128:129], off offset:656
	global_load_dwordx4 v[208:211], v[128:129], off offset:640
	s_waitcnt vmcnt(18)
; #define SCHEDB() __builtin_amdgcn_sched_barrier(0)
; DEVI void gemm_residual(const bfr* W, const bfr* X, int K, float* out, char* shm, const float* xp = nullptr, const float* xs = nullptr) {
;   gemm8_linear(W, 8, X, 128, K, shm, [&](f32x4 (&acc)[2][2][4][2], int pa, int pb) { EPI8_COORDS;
; #pragma unroll
;     for (int ai = 0; ai < 2; ++ai)
; #pragma unroll
;       for (int bj = 0; bj < 2; ++bj) {
; #pragma unroll
;         for (int n = 0; n < 2; ++n)
; #pragma unroll
;           for (int m = 0; m < 4; m += 2) {
;             const int tk = pb * 256 + bj * 128 + e_wc * 32 + n * 16 + e_fr;
;             const int fi = pa * 256 + ai * 128 + e_wr * 64 + (m + (e_fq & 1)) * 16 + (e_fq >> 1) * 8;
;             f32x4* d = reinterpret_cast<f32x4*>(out + (long)tk * DM + fi);
;             const f32x4* sp = xp ? reinterpret_cast<const f32x4*>((tk < 16384 ? xp + (long)tk * DM : xs + (long)(tk - 16384) * DM) + fi) : d;
;             f32x4 o0 = sp[0], o1 = sp[1];
;             const f32x4 va = acc[ai][bj][m][n], vb2 = acc[ai][bj][m + 1][n];
; #pragma unroll
;             for (int e = 0; e < 4; ++e) { auto rr = __builtin_amdgcn_permlane16_swap(__float_as_uint(va[e]), __float_as_uint(vb2[e]), false, false);
;               o0[e] += __uint_as_float(rr[0]); o1[e] += __uint_as_float(rr[1]); }
;             d[0] = o0; d[1] = o1; }
;         SCHEDB(); } });
	v_pk_add_f32 v[110:111], v[214:215], v[110:111]
	v_pk_add_f32 v[106:107], v[218:219], v[106:107]
	v_pk_add_f32 v[104:105], v[216:217], v[104:105]
	v_pk_add_f32 v[108:109], v[212:213], v[108:109]
	global_store_dwordx4 v[244:245], v[104:107], off
	global_store_dwordx4 v[244:245], v[108:111], off offset:16
	global_load_dwordx4 v[212:215], v[244:245], off offset:528
	global_load_dwordx4 v[216:219], v[244:245], off offset:512
	s_waitcnt vmcnt(20)
	v_pk_add_f32 v[98:99], v[222:223], v[98:99]
	v_pk_add_f32 v[102:103], v[226:227], v[102:103]
	v_pk_add_f32 v[100:101], v[224:225], v[100:101]
	v_pk_add_f32 v[96:97], v[220:221], v[96:97]
	global_store_dwordx4 v[244:245], v[100:103], off offset:128
	global_store_dwordx4 v[244:245], v[96:99], off offset:144
	global_load_dwordx4 v[220:223], v[244:245], off offset:656
	global_load_dwordx4 v[224:227], v[244:245], off offset:640
	s_waitcnt vmcnt(22)
	v_pk_add_f32 v[94:95], v[230:231], v[94:95]
	v_pk_add_f32 v[90:91], v[234:235], v[90:91]
	v_pk_add_f32 v[88:89], v[232:233], v[88:89]
	v_pk_add_f32 v[92:93], v[228:229], v[92:93]
	global_store_dwordx4 v[246:247], v[88:91], off
	global_store_dwordx4 v[246:247], v[92:95], off offset:16
	global_load_dwordx4 v[228:231], v[246:247], off offset:528
	global_load_dwordx4 v[232:235], v[246:247], off offset:512
	s_waitcnt vmcnt(24)
	v_pk_add_f32 v[86:87], v[238:239], v[86:87]
	v_pk_add_f32 v[82:83], v[242:243], v[82:83]
	v_pk_add_f32 v[80:81], v[240:241], v[80:81]
	v_pk_add_f32 v[84:85], v[236:237], v[84:85]
	global_store_dwordx4 v[246:247], v[80:83], off offset:128
	global_store_dwordx4 v[246:247], v[84:87], off offset:144
	global_load_dwordx4 v[236:239], v[246:247], off offset:656
	global_load_dwordx4 v[240:243], v[246:247], off offset:640
	s_waitcnt vmcnt(26)
	v_pk_add_f32 v[78:79], v[176:177], v[78:79]
	v_pk_add_f32 v[74:75], v[180:181], v[74:75]
	v_pk_add_f32 v[72:73], v[178:179], v[72:73]
	v_pk_add_f32 v[76:77], v[174:175], v[76:77]
	global_store_dwordx4 v[248:249], v[72:75], off
	global_store_dwordx4 v[248:249], v[76:79], off offset:16
	global_load_dwordx4 v[174:177], v[248:249], off offset:528
	global_load_dwordx4 v[178:181], v[248:249], off offset:512
	s_waitcnt vmcnt(28)
	v_pk_add_f32 v[66:67], v[184:185], v[66:67]
	v_pk_add_f32 v[70:71], v[188:189], v[70:71]
	v_pk_add_f32 v[68:69], v[186:187], v[68:69]
	v_pk_add_f32 v[64:65], v[182:183], v[64:65]
	global_store_dwordx4 v[248:249], v[68:71], off offset:128
	global_store_dwordx4 v[248:249], v[64:67], off offset:144
	global_load_dwordx4 v[182:185], v[248:249], off offset:656
	global_load_dwordx4 v[186:189], v[248:249], off offset:640
	s_waitcnt vmcnt(28)
	v_pk_add_f32 v[62:63], v[198:199], v[62:63]
	v_pk_add_f32 v[58:59], v[202:203], v[58:59]
	v_pk_add_f32 v[56:57], v[200:201], v[56:57]
	v_pk_add_f32 v[60:61], v[196:197], v[60:61]
	global_store_dwordx4 v[128:129], v[56:59], off offset:512
	global_store_dwordx4 v[128:129], v[60:63], off offset:528
	s_waitcnt vmcnt(26)
	v_pk_add_f32 v[54:55], v[206:207], v[54:55]
	v_pk_add_f32 v[50:51], v[210:211], v[50:51]
	v_pk_add_f32 v[48:49], v[208:209], v[48:49]
	v_pk_add_f32 v[52:53], v[204:205], v[52:53]
	global_store_dwordx4 v[128:129], v[48:51], off offset:640
	global_store_dwordx4 v[128:129], v[52:55], off offset:656
	s_waitcnt vmcnt(24)
	v_pk_add_f32 v[46:47], v[214:215], v[46:47]
	v_pk_add_f32 v[42:43], v[218:219], v[42:43]
	v_pk_add_f32 v[40:41], v[216:217], v[40:41]
	v_pk_add_f32 v[44:45], v[212:213], v[44:45]
	global_store_dwordx4 v[244:245], v[40:43], off offset:512
	global_store_dwordx4 v[244:245], v[44:47], off offset:528
	s_waitcnt vmcnt(22)
	v_pk_add_f32 v[34:35], v[222:223], v[34:35]
	v_pk_add_f32 v[38:39], v[226:227], v[38:39]
	v_pk_add_f32 v[36:37], v[224:225], v[36:37]
	v_pk_add_f32 v[32:33], v[220:221], v[32:33]
	global_store_dwordx4 v[244:245], v[36:39], off offset:640
	global_store_dwordx4 v[244:245], v[32:35], off offset:656
	s_waitcnt vmcnt(20)
	v_pk_add_f32 v[30:31], v[230:231], v[30:31]
	v_pk_add_f32 v[26:27], v[234:235], v[26:27]
	v_pk_add_f32 v[24:25], v[232:233], v[24:25]
	v_pk_add_f32 v[28:29], v[228:229], v[28:29]
	global_store_dwordx4 v[246:247], v[24:27], off offset:512
	global_store_dwordx4 v[246:247], v[28:31], off offset:528
	s_waitcnt vmcnt(18)
	v_pk_add_f32 v[22:23], v[238:239], v[22:23]
	v_pk_add_f32 v[18:19], v[242:243], v[18:19]
	v_pk_add_f32 v[16:17], v[240:241], v[16:17]
	v_pk_add_f32 v[20:21], v[236:237], v[20:21]
	global_store_dwordx4 v[246:247], v[16:19], off offset:640
	global_store_dwordx4 v[246:247], v[20:23], off offset:656
	s_waitcnt vmcnt(16)
	v_pk_add_f32 v[14:15], v[176:177], v[14:15]
	v_pk_add_f32 v[10:11], v[180:181], v[10:11]
	v_pk_add_f32 v[8:9], v[178:179], v[8:9]
	v_pk_add_f32 v[12:13], v[174:175], v[12:13]
	global_store_dwordx4 v[248:249], v[8:11], off offset:512
	global_store_dwordx4 v[248:249], v[12:15], off offset:528
	s_waitcnt vmcnt(14)
	v_pk_add_f32 v[2:3], v[184:185], v[2:3]
	v_pk_add_f32 v[6:7], v[188:189], v[6:7]
	v_pk_add_f32 v[4:5], v[186:187], v[4:5]
	v_pk_add_f32 v[0:1], v[182:183], v[0:1]
	global_store_dwordx4 v[248:249], v[4:7], off offset:640
	global_store_dwordx4 v[248:249], v[0:3], off offset:656
	s_and_b64 vcc, exec, s[6:7]
	s_mov_b32 s9, s68
	s_mov_b32 s2, s65
	s_cbranch_vccnz .LBB0_71

; DEVI unsigned cvtpk(float lo, float hi) { unsigned r; asm volatile("v_cvt_pk_bf16_f32 %0, %1, %2" : "=v"(r) : "v"(lo), "v"(hi)); return r; }
; DEVI int nblk() { int n = NBLK; asm volatile("" : "+s"(n)); return n; }
; DEVI int obid() { int b = blockIdx.x; asm volatile("" : "+s"(b)); return b; }
; DEVI void phase_rmsnorm(const float* __restrict__ x, const float* __restrict__ g, bfr* __restrict__ h, const float* __restrict__ xp = nullptr, const float* __restrict__ xs = nullptr) {
;     ...
;   for (int t = obid() * 8 + wid; t < T; t += nblk() * 8) {
;     const f32x4* xr = (const f32x4*)(xp ? (t < 16384 ? xp + (long)t * DM : xs + (long)(t - 16384) * DM) : x + (long)t * DM);
;     f32x4 v[8]; float ss = 0;
; #pragma unroll
;     for (int i = 0; i < 4; ++i) { v[2 * i] = xr[i * 128 + lane * 2]; v[2 * i + 1] = xr[i * 128 + lane * 2 + 1]; }
; #pragma unroll
;     for (int i = 0; i < 8; ++i) ss += v[i][0] * v[i][0] + v[i][1] * v[i][1] + v[i][2] * v[i][2] + v[i][3] * v[i][3];
;     ss = wave_sum(ss);
;     const float r = rsqrtf(ss * (1.f / DM) + EPS);
; #pragma unroll
;     for (int i = 0; i < 4; ++i) { const f32x4 g0 = ((const f32x4*)g)[i * 128 + lane * 2], g1 = ((const f32x4*)g)[i * 128 + lane * 2 + 1];
;       const f32x4 a = v[2 * i], c = v[2 * i + 1];
;       u32x4 w = {cvtpk(a[0] * r * g0[0], a[1] * r * g0[1]), cvtpk(a[2] * r * g0[2], a[3] * r * g0[3]),
;                  cvtpk(c[0] * r * g1[0], c[1] * r * g1[1]), cvtpk(c[2] * r * g1[2], c[3] * r * g1[3])};
;       *reinterpret_cast<u32x4*>(h + (long)t * DM + i * 512 + lane * 8) = w; }
;   }
.LBB0_208:
	v_mov_b32_e32 v232, v40
	v_mov_b32_e32 v233, 0
	v_lshlrev_b64 v[8:9], 13, v[232:233]
	v_lshl_add_u64 v[8:9], s[10:11], 0, v[8:9]
	v_lshl_add_u64 v[10:11], v[8:9], 0, v[166:167]
	global_load_dwordx4 v[32:35], v[10:11], off offset:16
	global_load_dwordx4 v[36:39], v[10:11], off
	global_load_dwordx4 v[24:27], v[10:11], off offset:2064
	global_load_dwordx4 v[28:31], v[10:11], off offset:2048
	v_mov_b32_e32 v51, v167
	v_lshl_add_u64 v[10:11], v[8:9], 0, v[50:51]
	global_load_dwordx4 v[20:23], v[10:11], off
	global_load_dwordx4 v[16:19], v[10:11], off offset:16
	v_mov_b32_e32 v53, v167
	v_lshl_add_u64 v[8:9], v[8:9], 0, v[52:53]
	global_load_dwordx4 v[12:15], v[8:9], off
	s_nop 0
	global_load_dwordx4 v[8:11], v[8:9], off offset:16
	s_movk_i32 s2, 0x100
	s_waitcnt vmcnt(0)
	v_mul_f32_e32 v53, v33, v33
	v_mul_f32_e32 v51, v37, v37
	v_fmac_f32_e32 v51, v36, v36
	v_fmac_f32_e32 v53, v32, v32
	v_fmac_f32_e32 v51, v38, v38
	v_fmac_f32_e32 v53, v34, v34
	v_fmac_f32_e32 v51, v39, v39
	v_fmac_f32_e32 v53, v35, v35
	v_add_f32_e32 v51, v51, v53
	v_mul_f32_e32 v53, v29, v29
	v_fmac_f32_e32 v53, v28, v28
	v_fmac_f32_e32 v53, v30, v30
	v_fmac_f32_e32 v53, v31, v31
	v_add_f32_e32 v51, v51, v53
	v_mul_f32_e32 v53, v25, v25
	v_mov_b32_e32 v62, v21
	v_mov_b32_e32 v63, v17
	v_fmac_f32_e32 v53, v24, v24
	v_mov_b32_e32 v54, v20
	v_mov_b32_e32 v55, v16
	v_pk_mul_f32 v[62:63], v[62:63], v[62:63]
	v_fmac_f32_e32 v53, v26, v26
	v_pk_fma_f32 v[54:55], v[54:55], v[54:55], v[62:63]
	v_mov_b32_e32 v62, v22
	v_mov_b32_e32 v63, v18
	v_fmac_f32_e32 v53, v27, v27
	v_pk_fma_f32 v[54:55], v[62:63], v[62:63], v[54:55]
	v_mov_b32_e32 v62, v23
	v_mov_b32_e32 v63, v19
	v_add_f32_e32 v51, v51, v53
	v_pk_fma_f32 v[54:55], v[62:63], v[62:63], v[54:55]
	v_mov_b32_e32 v62, v13
	v_add_f32_e32 v51, v51, v54
	v_mov_b32_e32 v63, v9
	v_add_f32_e32 v51, v51, v55
	v_mov_b32_e32 v54, v12
	v_mov_b32_e32 v55, v8
	v_pk_mul_f32 v[62:63], v[62:63], v[62:63]
	s_nop 0
	v_pk_fma_f32 v[54:55], v[54:55], v[54:55], v[62:63]
	v_mov_b32_e32 v62, v14
	v_mov_b32_e32 v63, v10
	v_pk_fma_f32 v[54:55], v[62:63], v[62:63], v[54:55]
	v_mov_b32_e32 v62, v15
	v_mov_b32_e32 v63, v11
	v_pk_fma_f32 v[54:55], v[62:63], v[62:63], v[54:55]
	s_nop 0
	v_add_f32_e32 v51, v51, v54
	v_add_f32_e32 v51, v51, v55
	ds_bpermute_b32 v53, v56, v51
	v_lshlrev_b64 v[54:55], 12, v[232:233]
	v_lshl_add_u64 v[54:55], v[42:43], 0, v[54:55]
	s_waitcnt lgkmcnt(0)
	v_add_f32_e32 v51, v51, v53
	ds_bpermute_b32 v53, v57, v51
	s_waitcnt lgkmcnt(0)
	v_add_f32_e32 v51, v51, v53
	ds_bpermute_b32 v53, v58, v51
	s_waitcnt lgkmcnt(0)
	v_add_f32_e32 v51, v51, v53
	ds_bpermute_b32 v53, v59, v51
	s_waitcnt lgkmcnt(0)
	v_add_f32_e32 v51, v51, v53
	ds_bpermute_b32 v53, v60, v51
	s_waitcnt lgkmcnt(0)
	v_add_f32_e32 v51, v51, v53
	ds_bpermute_b32 v53, v61, v51
	s_waitcnt lgkmcnt(0)
	v_add_f32_e32 v51, v51, v53
	v_fmamk_f32 v51, v51, 0x3a000000, v168
	v_cmp_gt_f32_e32 vcc, s6, v51
	v_mul_f32_e32 v53, 0x4b800000, v51
	s_nop 0
	v_cndmask_b32_e32 v51, v51, v53, vcc
	v_rsq_f32_e32 v51, v51
	s_nop 0
	v_mul_f32_e32 v53, 0x45800000, v51
	v_cndmask_b32_e32 v51, v51, v53, vcc
	v_mul_f32_e32 v36, v36, v51
	v_mul_f32_e32 v37, v37, v51
	v_mul_f32_e32 v36, v0, v36
	v_mul_f32_e32 v37, v1, v37
	v_cvt_pk_bf16_f32 v36, v36, v37
	v_mul_f32_e32 v37, v38, v51
	v_mul_f32_e32 v38, v39, v51
	v_mul_f32_e32 v32, v32, v51
	v_mul_f32_e32 v33, v33, v51
	v_mul_f32_e32 v37, v2, v37
	v_mul_f32_e32 v38, v3, v38
	v_mul_f32_e32 v32, v4, v32
	v_mul_f32_e32 v33, v5, v33
	v_cvt_pk_bf16_f32 v37, v37, v38
	v_cvt_pk_bf16_f32 v38, v32, v33
	v_mul_f32_e32 v32, v34, v51
	v_mul_f32_e32 v33, v35, v51
	v_mul_f32_e32 v32, v6, v32
	v_mul_f32_e32 v33, v7, v33
	v_cvt_pk_bf16_f32 v39, v32, v33
	global_store_dwordx4 v[54:55], v[36:39], off
	v_mul_f32_e32 v28, v28, v51
	v_mul_f32_e32 v29, v29, v51
	v_mul_f32_e32 v24, v24, v51
	v_mul_f32_e32 v25, v25, v51
	v_mul_f32_e32 v20, v20, v51
	v_mul_f32_e32 v21, v21, v51
	v_mul_f32_e32 v16, v16, v51
	v_mul_f32_e32 v17, v17, v51
	v_mul_f32_e32 v12, v12, v51
	v_mul_f32_e32 v13, v13, v51
	v_mul_f32_e32 v8, v8, v51
	v_mul_f32_e32 v9, v9, v51
	v_mul_f32_e32 v24, v212, v24
	v_mul_f32_e32 v28, v208, v28
	v_mul_f32_e32 v29, v209, v29
	v_cvt_pk_bf16_f32 v28, v28, v29
	v_mul_f32_e32 v29, v30, v51
	v_mul_f32_e32 v30, v31, v51
	v_mul_f32_e32 v29, v210, v29
	v_mul_f32_e32 v30, v211, v30
	v_mul_f32_e32 v25, v213, v25
	v_cvt_pk_bf16_f32 v29, v29, v30
	v_cvt_pk_bf16_f32 v30, v24, v25
	v_mul_f32_e32 v24, v26, v51
	v_mul_f32_e32 v25, v27, v51
	v_mul_f32_e32 v24, v214, v24
	v_mul_f32_e32 v25, v215, v25
	v_cvt_pk_bf16_f32 v31, v24, v25
	global_store_dwordx4 v[54:55], v[28:31], off offset:1024
	v_mul_f32_e32 v16, v16, v220
	v_mul_f32_e32 v20, v20, v216
	v_mul_f32_e32 v21, v21, v217
	v_cvt_pk_bf16_f32 v20, v20, v21
	v_mul_f32_e32 v21, v22, v51
	v_mul_f32_e32 v22, v23, v51
	v_mul_f32_e32 v21, v21, v218
	v_mul_f32_e32 v22, v22, v219
	v_mul_f32_e32 v17, v17, v221
	v_cvt_pk_bf16_f32 v21, v21, v22
	v_cvt_pk_bf16_f32 v22, v16, v17
	v_mul_f32_e32 v16, v18, v51
	v_mul_f32_e32 v17, v19, v51
	v_mul_f32_e32 v16, v16, v222
	v_mul_f32_e32 v17, v17, v223
	v_cvt_pk_bf16_f32 v23, v16, v17
	global_store_dwordx4 v[54:55], v[20:23], off offset:2048
	v_mul_f32_e32 v8, v8, v228
	v_mul_f32_e32 v12, v12, v224
	v_mul_f32_e32 v13, v13, v225
	v_cvt_pk_bf16_f32 v12, v12, v13
	v_mul_f32_e32 v13, v14, v51
	v_mul_f32_e32 v14, v15, v51
	v_mul_f32_e32 v13, v13, v226
	v_mul_f32_e32 v14, v14, v227
	v_mul_f32_e32 v9, v9, v229
	v_cvt_pk_bf16_f32 v13, v13, v14
	v_cvt_pk_bf16_f32 v14, v8, v9
	v_mul_f32_e32 v8, v10, v51
	v_mul_f32_e32 v9, v11, v51
	v_mul_f32_e32 v8, v8, v230
	v_mul_f32_e32 v9, v9, v231
	v_cvt_pk_bf16_f32 v15, v8, v9
	global_store_dwordx4 v[54:55], v[12:15], off offset:3072
	s_nop 0
	v_lshl_add_u32 v40, s2, 3, v40
	v_cmp_lt_i32_e32 vcc, s7, v40
	s_or_b64 s[4:5], vcc, s[4:5]
	s_andn2_b64 exec, exec, s[4:5]
	s_cbranch_execnz .LBB0_208

; DEVI void gemm_residual(const bfr* W, const bfr* X, int K, float* out, char* shm, const float* xp = nullptr, const float* xs = nullptr) {
;     ...
;             const int tk = pb * 256 + bj * 128 + e_wc * 32 + n * 16 + e_fr;
;             const int fi = pa * 256 + ai * 128 + e_wr * 64 + (m + (e_fq & 1)) * 16 + (e_fq >> 1) * 8;
;             f32x4* d = reinterpret_cast<f32x4*>(out + (long)tk * DM + fi);
;             const f32x4* sp = xp ? reinterpret_cast<const f32x4*>((tk < 16384 ? xp + (long)tk * DM : xs + (long)(tk - 16384) * DM) + fi) : d;
;             f32x4 o0 = sp[0], o1 = sp[1];
;             const f32x4 va = acc[ai][bj][m][n], vb2 = acc[ai][bj][m + 1][n];
; #pragma unroll
;             for (int e = 0; e < 4; ++e) { auto rr = __builtin_amdgcn_permlane16_swap(__float_as_uint(va[e]), __float_as_uint(vb2[e]), false, false);
;               o0[e] += __uint_as_float(rr[0]); o1[e] += __uint_as_float(rr[1]); }
;             d[0] = o0; d[1] = o1; }
.LBB0_278:
	v_mov_b32_e32 v128, v164
	v_lshrrev_b32_e32 v130, 1, v128
	v_and_b32_e32 v129, 15, v128
	v_and_b32_e32 v130, 0x60, v130
	v_or3_b32 v130, v129, v130, s10
	v_ashrrev_i32_e32 v129, 2, v128
	v_and_b32_e32 v129, 0xffffffc0, v129
	v_lshrrev_b32_e32 v131, 2, v128
	v_and_or_b32 v128, v128, 16, s8
	v_add_u32_e32 v128, v128, v129
	v_and_or_b32 v128, v131, 8, v128
	v_ashrrev_i32_e32 v131, 31, v130
	v_readlane_b32 s8, v255, 2
	v_lshlrev_b64 v[132:133], 13, v[130:131]
	v_readlane_b32 s10, v255, 4
	v_readlane_b32 s11, v255, 5
	s_nop 1
	v_ashrrev_i32_e32 v129, 31, v128
	v_lshl_add_u64 v[134:135], s[10:11], 0, v[132:133]
	v_lshlrev_b64 v[132:133], 2, v[128:129]
	v_lshl_add_u64 v[128:129], v[134:135], 0, v[132:133]
	v_readlane_b32 s9, v255, 3
	s_nop 1
	v_or_b32_e32 v244, 16, v130
	v_ashrrev_i32_e32 v245, 31, v244
	v_lshlrev_b64 v[244:245], 13, v[244:245]
	v_lshl_add_u64 v[244:245], s[10:11], 0, v[244:245]
	v_lshl_add_u64 v[244:245], v[244:245], 0, v[132:133]
	v_or_b32_e32 v246, 0x80, v130
	v_ashrrev_i32_e32 v247, 31, v246
	v_lshlrev_b64 v[246:247], 13, v[246:247]
	v_lshl_add_u64 v[246:247], s[10:11], 0, v[246:247]
	v_lshl_add_u64 v[246:247], v[246:247], 0, v[132:133]
	v_or_b32_e32 v248, 0x90, v130
	v_ashrrev_i32_e32 v249, 31, v248
	v_lshlrev_b64 v[248:249], 13, v[248:249]
	v_lshl_add_u64 v[248:249], s[10:11], 0, v[248:249]
	v_lshl_add_u64 v[248:249], v[248:249], 0, v[132:133]
	global_load_dwordx4 v[196:199], v[128:129], off offset:16
	global_load_dwordx4 v[200:203], v[128:129], off
	global_load_dwordx4 v[204:207], v[128:129], off offset:144
	global_load_dwordx4 v[208:211], v[128:129], off offset:128
	global_load_dwordx4 v[212:215], v[244:245], off offset:16
	global_load_dwordx4 v[216:219], v[244:245], off
	global_load_dwordx4 v[220:223], v[244:245], off offset:144
	global_load_dwordx4 v[224:227], v[244:245], off offset:128
	global_load_dwordx4 v[228:231], v[246:247], off offset:16
	global_load_dwordx4 v[232:235], v[246:247], off
	global_load_dwordx4 v[236:239], v[246:247], off offset:144
	global_load_dwordx4 v[240:243], v[246:247], off offset:128
	global_load_dwordx4 v[174:177], v[248:249], off offset:16
	global_load_dwordx4 v[178:181], v[248:249], off
	global_load_dwordx4 v[182:185], v[248:249], off offset:144
	global_load_dwordx4 v[186:189], v[248:249], off offset:128
	v_permlane16_swap_b32_e32 v120, v124
	v_permlane16_swap_b32_e32 v121, v125
	v_permlane16_swap_b32_e32 v122, v126
	v_permlane16_swap_b32_e32 v123, v127
	v_permlane16_swap_b32_e32 v112, v116
	v_permlane16_swap_b32_e32 v113, v117
	v_permlane16_swap_b32_e32 v114, v118
	v_permlane16_swap_b32_e32 v115, v119
	v_permlane16_swap_b32_e32 v104, v108
	v_permlane16_swap_b32_e32 v105, v109
	v_permlane16_swap_b32_e32 v106, v110
	v_permlane16_swap_b32_e32 v107, v111
	v_permlane16_swap_b32_e32 v100, v96
	v_permlane16_swap_b32_e32 v101, v97
	v_permlane16_swap_b32_e32 v102, v98
	v_permlane16_swap_b32_e32 v103, v99
	v_permlane16_swap_b32_e32 v88, v92
	v_permlane16_swap_b32_e32 v89, v93
	v_permlane16_swap_b32_e32 v90, v94
	v_permlane16_swap_b32_e32 v91, v95
	v_permlane16_swap_b32_e32 v80, v84
	v_permlane16_swap_b32_e32 v81, v85
	v_permlane16_swap_b32_e32 v82, v86
	v_permlane16_swap_b32_e32 v83, v87
	v_permlane16_swap_b32_e32 v72, v76
	v_permlane16_swap_b32_e32 v73, v77
	v_permlane16_swap_b32_e32 v74, v78
	v_permlane16_swap_b32_e32 v75, v79
	v_permlane16_swap_b32_e32 v68, v64
	v_permlane16_swap_b32_e32 v69, v65
	v_permlane16_swap_b32_e32 v70, v66
	v_permlane16_swap_b32_e32 v71, v67
	v_permlane16_swap_b32_e32 v56, v60
	v_permlane16_swap_b32_e32 v57, v61
	v_permlane16_swap_b32_e32 v58, v62
	v_permlane16_swap_b32_e32 v59, v63
	v_permlane16_swap_b32_e32 v48, v52
	v_permlane16_swap_b32_e32 v49, v53
	v_permlane16_swap_b32_e32 v50, v54
	v_permlane16_swap_b32_e32 v51, v55
	v_permlane16_swap_b32_e32 v40, v44
	v_permlane16_swap_b32_e32 v41, v45
	v_permlane16_swap_b32_e32 v42, v46
	v_permlane16_swap_b32_e32 v43, v47
	v_permlane16_swap_b32_e32 v36, v32
	v_permlane16_swap_b32_e32 v37, v33
	v_permlane16_swap_b32_e32 v38, v34
	v_permlane16_swap_b32_e32 v39, v35
	v_permlane16_swap_b32_e32 v24, v28
	v_permlane16_swap_b32_e32 v25, v29
	v_permlane16_swap_b32_e32 v26, v30
	v_permlane16_swap_b32_e32 v27, v31
	v_permlane16_swap_b32_e32 v16, v20
	v_permlane16_swap_b32_e32 v17, v21
	v_permlane16_swap_b32_e32 v18, v22
	v_permlane16_swap_b32_e32 v19, v23
	v_permlane16_swap_b32_e32 v8, v12
	v_permlane16_swap_b32_e32 v9, v13
	v_permlane16_swap_b32_e32 v10, v14
	v_permlane16_swap_b32_e32 v11, v15
	v_permlane16_swap_b32_e32 v4, v0
	v_permlane16_swap_b32_e32 v5, v1
	v_permlane16_swap_b32_e32 v6, v2
	v_permlane16_swap_b32_e32 v7, v3
	s_waitcnt vmcnt(14)
	v_pk_add_f32 v[126:127], v[198:199], v[126:127]
	v_pk_add_f32 v[122:123], v[202:203], v[122:123]
	v_pk_add_f32 v[120:121], v[200:201], v[120:121]
	v_pk_add_f32 v[124:125], v[196:197], v[124:125]
	global_store_dwordx4 v[128:129], v[120:123], off
	global_store_dwordx4 v[128:129], v[124:127], off offset:16
	global_load_dwordx4 v[196:199], v[128:129], off offset:528
	global_load_dwordx4 v[200:203], v[128:129], off offset:512
	s_waitcnt vmcnt(16)
	v_pk_add_f32 v[118:119], v[206:207], v[118:119]
	v_pk_add_f32 v[114:115], v[210:211], v[114:115]
	v_pk_add_f32 v[112:113], v[208:209], v[112:113]
	v_pk_add_f32 v[116:117], v[204:205], v[116:117]
	global_store_dwordx4 v[128:129], v[112:115], off offset:128
	global_store_dwordx4 v[128:129], v[116:119], off offset:144
	global_load_dwordx4 v[204:207], v[128:129], off offset:656
	global_load_dwordx4 v[208:211], v[128:129], off offset:640
	s_waitcnt vmcnt(18)
; #define SCHEDB() __builtin_amdgcn_sched_barrier(0)
; DEVI void gemm_residual(const bfr* W, const bfr* X, int K, float* out, char* shm, const float* xp = nullptr, const float* xs = nullptr) {
;     ...
;             const int tk = pb * 256 + bj * 128 + e_wc * 32 + n * 16 + e_fr;
;             const int fi = pa * 256 + ai * 128 + e_wr * 64 + (m + (e_fq & 1)) * 16 + (e_fq >> 1) * 8;
;             f32x4* d = reinterpret_cast<f32x4*>(out + (long)tk * DM + fi);
;             const f32x4* sp = xp ? reinterpret_cast<const f32x4*>((tk < 16384 ? xp + (long)tk * DM : xs + (long)(tk - 16384) * DM) + fi) : d;
;             f32x4 o0 = sp[0], o1 = sp[1];
;             const f32x4 va = acc[ai][bj][m][n], vb2 = acc[ai][bj][m + 1][n];
; #pragma unroll
;             for (int e = 0; e < 4; ++e) { auto rr = __builtin_amdgcn_permlane16_swap(__float_as_uint(va[e]), __float_as_uint(vb2[e]), false, false);
;               o0[e] += __uint_as_float(rr[0]); o1[e] += __uint_as_float(rr[1]); }
;             d[0] = o0; d[1] = o1; }
;         SCHEDB(); } });
	v_pk_add_f32 v[110:111], v[214:215], v[110:111]
	v_pk_add_f32 v[106:107], v[218:219], v[106:107]
	v_pk_add_f32 v[104:105], v[216:217], v[104:105]
	v_pk_add_f32 v[108:109], v[212:213], v[108:109]
	global_store_dwordx4 v[244:245], v[104:107], off
	global_store_dwordx4 v[244:245], v[108:111], off offset:16
	global_load_dwordx4 v[212:215], v[244:245], off offset:528
	global_load_dwordx4 v[216:219], v[244:245], off offset:512
	s_waitcnt vmcnt(20)
	v_pk_add_f32 v[98:99], v[222:223], v[98:99]
	v_pk_add_f32 v[102:103], v[226:227], v[102:103]
	v_pk_add_f32 v[100:101], v[224:225], v[100:101]
	v_pk_add_f32 v[96:97], v[220:221], v[96:97]
	global_store_dwordx4 v[244:245], v[100:103], off offset:128
	global_store_dwordx4 v[244:245], v[96:99], off offset:144
	global_load_dwordx4 v[220:223], v[244:245], off offset:656
	global_load_dwordx4 v[224:227], v[244:245], off offset:640
	s_waitcnt vmcnt(22)
	v_pk_add_f32 v[94:95], v[230:231], v[94:95]
	v_pk_add_f32 v[90:91], v[234:235], v[90:91]
	v_pk_add_f32 v[88:89], v[232:233], v[88:89]
	v_pk_add_f32 v[92:93], v[228:229], v[92:93]
	global_store_dwordx4 v[246:247], v[88:91], off
	global_store_dwordx4 v[246:247], v[92:95], off offset:16
	global_load_dwordx4 v[228:231], v[246:247], off offset:528
	global_load_dwordx4 v[232:235], v[246:247], off offset:512
	s_waitcnt vmcnt(24)
	v_pk_add_f32 v[86:87], v[238:239], v[86:87]
	v_pk_add_f32 v[82:83], v[242:243], v[82:83]
	v_pk_add_f32 v[80:81], v[240:241], v[80:81]
	v_pk_add_f32 v[84:85], v[236:237], v[84:85]
	global_store_dwordx4 v[246:247], v[80:83], off offset:128
	global_store_dwordx4 v[246:247], v[84:87], off offset:144
	global_load_dwordx4 v[236:239], v[246:247], off offset:656
	global_load_dwordx4 v[240:243], v[246:247], off offset:640
	s_waitcnt vmcnt(26)
	v_pk_add_f32 v[78:79], v[176:177], v[78:79]
	v_pk_add_f32 v[74:75], v[180:181], v[74:75]
	v_pk_add_f32 v[72:73], v[178:179], v[72:73]
	v_pk_add_f32 v[76:77], v[174:175], v[76:77]
	global_store_dwordx4 v[248:249], v[72:75], off
	global_store_dwordx4 v[248:249], v[76:79], off offset:16
	global_load_dwordx4 v[174:177], v[248:249], off offset:528
	global_load_dwordx4 v[178:181], v[248:249], off offset:512
	s_waitcnt vmcnt(28)
	v_pk_add_f32 v[66:67], v[184:185], v[66:67]
	v_pk_add_f32 v[70:71], v[188:189], v[70:71]
	v_pk_add_f32 v[68:69], v[186:187], v[68:69]
	v_pk_add_f32 v[64:65], v[182:183], v[64:65]
	global_store_dwordx4 v[248:249], v[68:71], off offset:128
	global_store_dwordx4 v[248:249], v[64:67], off offset:144
	global_load_dwordx4 v[182:185], v[248:249], off offset:656
	global_load_dwordx4 v[186:189], v[248:249], off offset:640
	s_waitcnt vmcnt(28)
	v_pk_add_f32 v[62:63], v[198:199], v[62:63]
	v_pk_add_f32 v[58:59], v[202:203], v[58:59]
	v_pk_add_f32 v[56:57], v[200:201], v[56:57]
	v_pk_add_f32 v[60:61], v[196:197], v[60:61]
	global_store_dwordx4 v[128:129], v[56:59], off offset:512
	global_store_dwordx4 v[128:129], v[60:63], off offset:528
	s_waitcnt vmcnt(26)
	v_pk_add_f32 v[54:55], v[206:207], v[54:55]
	v_pk_add_f32 v[50:51], v[210:211], v[50:51]
	v_pk_add_f32 v[48:49], v[208:209], v[48:49]
	v_pk_add_f32 v[52:53], v[204:205], v[52:53]
	global_store_dwordx4 v[128:129], v[48:51], off offset:640
	global_store_dwordx4 v[128:129], v[52:55], off offset:656
	s_waitcnt vmcnt(24)
	v_pk_add_f32 v[46:47], v[214:215], v[46:47]
	v_pk_add_f32 v[42:43], v[218:219], v[42:43]
	v_pk_add_f32 v[40:41], v[216:217], v[40:41]
	v_pk_add_f32 v[44:45], v[212:213], v[44:45]
	global_store_dwordx4 v[244:245], v[40:43], off offset:512
	global_store_dwordx4 v[244:245], v[44:47], off offset:528
	s_waitcnt vmcnt(22)
	v_pk_add_f32 v[34:35], v[222:223], v[34:35]
	v_pk_add_f32 v[38:39], v[226:227], v[38:39]
	v_pk_add_f32 v[36:37], v[224:225], v[36:37]
	v_pk_add_f32 v[32:33], v[220:221], v[32:33]
	global_store_dwordx4 v[244:245], v[36:39], off offset:640
	global_store_dwordx4 v[244:245], v[32:35], off offset:656
	s_waitcnt vmcnt(20)
	v_pk_add_f32 v[30:31], v[230:231], v[30:31]
	v_pk_add_f32 v[26:27], v[234:235], v[26:27]
	v_pk_add_f32 v[24:25], v[232:233], v[24:25]
	v_pk_add_f32 v[28:29], v[228:229], v[28:29]
	global_store_dwordx4 v[246:247], v[24:27], off offset:512
	global_store_dwordx4 v[246:247], v[28:31], off offset:528
	s_waitcnt vmcnt(18)
	v_pk_add_f32 v[22:23], v[238:239], v[22:23]
	v_pk_add_f32 v[18:19], v[242:243], v[18:19]
	v_pk_add_f32 v[16:17], v[240:241], v[16:17]
	v_pk_add_f32 v[20:21], v[236:237], v[20:21]
	global_store_dwordx4 v[246:247], v[16:19], off offset:640
	global_store_dwordx4 v[246:247], v[20:23], off offset:656
	s_waitcnt vmcnt(16)
	v_pk_add_f32 v[14:15], v[176:177], v[14:15]
	v_pk_add_f32 v[10:11], v[180:181], v[10:11]
	v_pk_add_f32 v[8:9], v[178:179], v[8:9]
	v_pk_add_f32 v[12:13], v[174:175], v[12:13]
	global_store_dwordx4 v[248:249], v[8:11], off offset:512
	global_store_dwordx4 v[248:249], v[12:15], off offset:528
	s_waitcnt vmcnt(14)
	v_pk_add_f32 v[2:3], v[184:185], v[2:3]
	v_pk_add_f32 v[6:7], v[188:189], v[6:7]
	v_pk_add_f32 v[4:5], v[186:187], v[4:5]
	v_pk_add_f32 v[0:1], v[182:183], v[0:1]
	global_store_dwordx4 v[248:249], v[4:7], off offset:640
	global_store_dwordx4 v[248:249], v[0:3], off offset:656
	s_and_b64 vcc, exec, s[6:7]
	s_mov_b32 s9, s72
	s_mov_b32 s2, s69
	s_cbranch_vccnz .LBB0_291

; DEVI int obid() { int b = blockIdx.x; asm volatile("" : "+s"(b)); return b; }
; DEVI int otid() { int t = threadIdx.x; asm volatile("" : "+v"(t)); return t; }
; #define P8_STAGE(P,BASE,br,kt) do{const bfr* _ub=(BASE)+((long)(br)*K+(long)(kt)*BK); \
;     __builtin_amdgcn_global_load_lds((const unsigned*)(_ub+so0),(unsigned*)((char*)(P)+wid*1024),16,0,0); \
;     __builtin_amdgcn_global_load_lds((const unsigned*)(_ub+so1),(unsigned*)((char*)(P)+wid*1024+8192),16,0,0);}while(0)
; DEVI void gemm8_issue0(const bfr* __restrict__ A, const bfr* __restrict__ Bt, int K, int brow, int bcol, char* shmc) {
;   bfr* shm = (bfr*)shmc;
;   const int tid = otid(), wid = tid >> 6;
;   unsigned so0, so1;
;   { int _r, _c; stage_rc(tid * 16, _r, _c); so0 = (unsigned)(_r * K + _c); stage_rc(tid * 16 + 8192, _r, _c); so1 = (unsigned)(_r * K + _c); }
;   P8_STAGE(P8_SB(0,0),Bt,bcol,0); P8_STAGE(P8_SA(0,0),A,brow,0);
;   P8_STAGE(P8_SB(0,1),Bt,bcol+128,0); P8_STAGE(P8_SA(0,1),A,brow+128,0);
; }
; DEVI void tile_decode(int t, int ntiles, int ntA, int& pa, int& pb) {
;   int tp = xcd_perm2(t, ntiles);
;   int grp = tp / (16 * ntA), rem = tp % (16 * ntA); pa = rem >> 4; pb = grp * 16 + (rem & 15);
; }
; template <class EPI>
; DEVI void gemm8_linear(const bfr* A, int ntA, const bfr* B, int ntB, int K, char* shm, EPI epi) {
;   const int ntiles = ntA * ntB;
;   int t = obid(), pa = 0, pb = 0;
;   if (t < ntiles) { tile_decode(t, ntiles, ntA, pa, pb); gemm8_issue0(A, B, K, pa * 256, pb * 256, shm); }
.LBB0_373:
	v_readlane_b32 s4, v255, 25
	v_readlane_b32 s5, v255, 26
	s_ashr_i32 s5, s4, 31
	s_mov_b32 s2, s4
	s_lshl_b64 s[4:5], s[4:5], 25
	v_writelane_b32 v255, s2, 25
	s_add_u32 s1, s86, s4
	v_mov_b32_e32 v0, v164
	v_writelane_b32 v255, s3, 26
	s_addc_u32 s2, s87, s5
	s_add_u32 s31, s1, 0xba00000
	s_addc_u32 s64, s2, 0
	s_add_u32 s65, s86, 0x1be90000
	s_addc_u32 s68, s87, 0
	s_ashr_i32 s1, s0, 31
	s_lshr_b32 s1, s1, 25
	s_add_i32 s1, s0, s1
	s_ashr_i32 s4, s1, 7
	s_and_b32 s1, s1, 0xffffff80
	s_sub_i32 s0, s0, s1
	s_ashr_i32 s2, s0, 4
	s_lshl_b32 s1, s4, 4
	s_and_b32 s0, s0, 15
	s_or_b32 s11, s0, s1
	s_sub_i32 s11, 0x7f, s11
	v_lshlrev_b32_e32 v1, 4, v0
	v_and_b32_e32 v2, 32, v0
	v_bitop3_b32 v2, v1, v2, 48 bitop3:0x6c
	s_lshl_b32 s4, s11, 8
	v_lshrrev_b32_e32 v3, 3, v0
	v_bfe_u32 v4, v0, 2, 4
	v_lshrrev_b32_e32 v0, 1, v0
	v_lshrrev_b32_e32 v2, 1, v2
	s_mov_b32 s1, 0x7fff0
	v_and_or_b32 v0, v0, 32, v2
	v_add_u32_e32 v2, 0x2000, v1
	s_ashr_i32 s5, s4, 31
	s_lshl_b32 s0, s2, 8
	v_and_or_b32 v3, v3, s1, v4
	v_lshrrev_b32_e32 v2, 7, v2
	s_lshl_b64 s[6:7], s[4:5], 14
	v_and_b32_e32 v6, 0xfffffc00, v1
	v_lshl_or_b32 v166, v3, 13, v0
	v_and_or_b32 v2, v2, s1, v4
	s_add_u32 s6, s65, s6
	v_add_u32_e32 v1, 0x10000, v6
	v_lshl_or_b32 v0, v2, 13, v0
	s_addc_u32 s7, s68, s7
	v_lshlrev_b64 v[2:3], 1, v[166:167]
	v_readfirstlane_b32 s1, v1
	v_add_u32_e32 v7, 0x12000, v6
	v_lshl_add_u64 v[4:5], s[6:7], 0, v[2:3]
	s_mov_b32 m0, s1
	v_mov_b32_e32 v1, v167
	v_readfirstlane_b32 s1, v7
	global_load_lds_dwordx4 v[4:5], off
	v_lshlrev_b64 v[0:1], 1, v[0:1]
	s_mov_b32 m0, s1
	s_ashr_i32 s1, s0, 31
	v_lshl_add_u64 v[4:5], s[6:7], 0, v[0:1]
	s_lshl_b64 s[6:7], s[0:1], 14
	s_add_u32 s6, s31, s6
	s_addc_u32 s7, s64, s7
	s_bitset1_b32 s4, 7
	s_ashr_i32 s5, s4, 31
	v_readfirstlane_b32 s1, v6
	v_add_u32_e32 v7, 0x2000, v6
	s_lshl_b64 s[4:5], s[4:5], 14
	global_load_lds_dwordx4 v[4:5], off
	v_lshl_add_u64 v[4:5], s[6:7], 0, v[2:3]
	s_mov_b32 m0, s1
	v_readfirstlane_b32 s1, v7
	s_add_u32 s4, s65, s4
	v_add_u32_e32 v7, 0x14000, v6
	global_load_lds_dwordx4 v[4:5], off
	v_lshl_add_u64 v[4:5], s[6:7], 0, v[0:1]
	s_mov_b32 m0, s1
	s_addc_u32 s5, s68, s5
	v_readfirstlane_b32 s1, v7
	v_add_u32_e32 v7, 0x16000, v6
	global_load_lds_dwordx4 v[4:5], off
	v_lshl_add_u64 v[4:5], s[4:5], 0, v[2:3]
	s_mov_b32 m0, s1
	v_readfirstlane_b32 s1, v7
	s_bitset1_b32 s0, 7
	global_load_lds_dwordx4 v[4:5], off
	s_mov_b32 m0, s1
	s_ashr_i32 s1, s0, 31
	v_lshl_add_u64 v[4:5], s[4:5], 0, v[0:1]
	s_lshl_b64 s[0:1], s[0:1], 14
	global_load_lds_dwordx4 v[4:5], off
	s_add_u32 s0, s31, s0
	v_add_u32_e32 v4, 0x4000, v6
	s_addc_u32 s1, s64, s1
	v_readfirstlane_b32 s4, v4
	v_lshl_add_u64 v[2:3], s[0:1], 0, v[2:3]
	s_mov_b32 m0, s4
	v_lshl_add_u64 v[0:1], s[0:1], 0, v[0:1]
	global_load_lds_dwordx4 v[2:3], off
	v_add_u32_e32 v2, 0x6000, v6
	s_nop 0
	v_readfirstlane_b32 s0, v2
	s_mov_b32 m0, s0
	s_add_i32 s0, s73, s91
	global_load_lds_dwordx4 v[0:1], off
	s_ashr_i32 s1, s0, 31
	s_lshl_b64 s[6:7], s[0:1], 25
	s_branch .LBB0_375
.LBB0_374:
	v_mov_b32_e32 v128, v164
	v_readlane_b32 s92, v255, 2
	v_lshrrev_b32_e32 v130, 1, v128
	v_and_b32_e32 v129, 15, v128
	v_and_b32_e32 v130, 0x60, v130
	v_or3_b32 v130, v129, v130, s34
	v_ashrrev_i32_e32 v129, 2, v128
	v_and_b32_e32 v129, 0xffffffc0, v129
	v_lshrrev_b32_e32 v131, 2, v128
	v_and_or_b32 v128, v128, 16, s10
	v_add_u32_e32 v128, v128, v129
	v_and_or_b32 v128, v131, 8, v128
	v_ashrrev_i32_e32 v131, 31, v130
	v_lshlrev_b64 v[132:133], 13, v[130:131]
	v_readlane_b32 s94, v255, 4
	v_readlane_b32 s95, v255, 5
	s_nop 1
	v_ashrrev_i32_e32 v129, 31, v128
	v_lshl_add_u64 v[134:135], s[94:95], 0, v[132:133]
	v_lshlrev_b64 v[132:133], 2, v[128:129]
	v_lshl_add_u64 v[128:129], v[134:135], 0, v[132:133]
	v_readlane_b32 s93, v255, 3
	s_nop 1
	v_or_b32_e32 v244, 16, v130
	v_ashrrev_i32_e32 v245, 31, v244
	v_lshlrev_b64 v[244:245], 13, v[244:245]
	v_lshl_add_u64 v[244:245], s[94:95], 0, v[244:245]
	v_lshl_add_u64 v[244:245], v[244:245], 0, v[132:133]
	v_or_b32_e32 v246, 0x80, v130
	v_ashrrev_i32_e32 v247, 31, v246
	v_lshlrev_b64 v[246:247], 13, v[246:247]
	v_lshl_add_u64 v[246:247], s[94:95], 0, v[246:247]
	v_lshl_add_u64 v[246:247], v[246:247], 0, v[132:133]
	v_or_b32_e32 v248, 0x90, v130
	v_ashrrev_i32_e32 v249, 31, v248
	v_lshlrev_b64 v[248:249], 13, v[248:249]
	v_lshl_add_u64 v[248:249], s[94:95], 0, v[248:249]
	v_lshl_add_u64 v[248:249], v[248:249], 0, v[132:133]
	global_load_dwordx4 v[196:199], v[128:129], off offset:16
	global_load_dwordx4 v[200:203], v[128:129], off
	global_load_dwordx4 v[204:207], v[128:129], off offset:144
	global_load_dwordx4 v[208:211], v[128:129], off offset:128
	global_load_dwordx4 v[212:215], v[244:245], off offset:16
	global_load_dwordx4 v[216:219], v[244:245], off
	global_load_dwordx4 v[220:223], v[244:245], off offset:144
	global_load_dwordx4 v[224:227], v[244:245], off offset:128
	global_load_dwordx4 v[228:231], v[246:247], off offset:16
	global_load_dwordx4 v[232:235], v[246:247], off
	global_load_dwordx4 v[236:239], v[246:247], off offset:144
	global_load_dwordx4 v[240:243], v[246:247], off offset:128
	global_load_dwordx4 v[174:177], v[248:249], off offset:16
	global_load_dwordx4 v[178:181], v[248:249], off
	global_load_dwordx4 v[182:185], v[248:249], off offset:144
	global_load_dwordx4 v[186:189], v[248:249], off offset:128
	v_permlane16_swap_b32_e32 v120, v124
	v_permlane16_swap_b32_e32 v121, v125
	v_permlane16_swap_b32_e32 v122, v126
	v_permlane16_swap_b32_e32 v123, v127
	v_permlane16_swap_b32_e32 v112, v116
	v_permlane16_swap_b32_e32 v113, v117
	v_permlane16_swap_b32_e32 v114, v118
	v_permlane16_swap_b32_e32 v115, v119
; DEVI void gemm_residual(const bfr* W, const bfr* X, int K, float* out, char* shm, const float* xp = nullptr, const float* xs = nullptr) {
;     ...
;             for (int e = 0; e < 4; ++e) { auto rr = __builtin_amdgcn_permlane16_swap(__float_as_uint(va[e]), __float_as_uint(vb2[e]), false, false);
;               o0[e] += __uint_as_float(rr[0]); o1[e] += __uint_as_float(rr[1]); }
;             d[0] = o0; d[1] = o1; }
	v_permlane16_swap_b32_e32 v104, v108
	v_permlane16_swap_b32_e32 v105, v109
	v_permlane16_swap_b32_e32 v106, v110
	v_permlane16_swap_b32_e32 v107, v111
	v_permlane16_swap_b32_e32 v100, v96
	v_permlane16_swap_b32_e32 v101, v97
	v_permlane16_swap_b32_e32 v102, v98
	v_permlane16_swap_b32_e32 v103, v99
	v_permlane16_swap_b32_e32 v88, v92
	v_permlane16_swap_b32_e32 v89, v93
	v_permlane16_swap_b32_e32 v90, v94
	v_permlane16_swap_b32_e32 v91, v95
	v_permlane16_swap_b32_e32 v80, v84
	v_permlane16_swap_b32_e32 v81, v85
	v_permlane16_swap_b32_e32 v82, v86
	v_permlane16_swap_b32_e32 v83, v87
	v_permlane16_swap_b32_e32 v72, v76
	v_permlane16_swap_b32_e32 v73, v77
	v_permlane16_swap_b32_e32 v74, v78
	v_permlane16_swap_b32_e32 v75, v79
	v_permlane16_swap_b32_e32 v68, v64
	v_permlane16_swap_b32_e32 v69, v65
	v_permlane16_swap_b32_e32 v70, v66
	v_permlane16_swap_b32_e32 v71, v67
	v_permlane16_swap_b32_e32 v56, v60
	v_permlane16_swap_b32_e32 v57, v61
	v_permlane16_swap_b32_e32 v58, v62
	v_permlane16_swap_b32_e32 v59, v63
	v_permlane16_swap_b32_e32 v48, v52
	v_permlane16_swap_b32_e32 v49, v53
	v_permlane16_swap_b32_e32 v50, v54
	v_permlane16_swap_b32_e32 v51, v55
	v_permlane16_swap_b32_e32 v40, v44
	v_permlane16_swap_b32_e32 v41, v45
	v_permlane16_swap_b32_e32 v42, v46
	v_permlane16_swap_b32_e32 v43, v47
	v_permlane16_swap_b32_e32 v36, v32
	v_permlane16_swap_b32_e32 v37, v33
	v_permlane16_swap_b32_e32 v38, v34
	v_permlane16_swap_b32_e32 v39, v35
	v_permlane16_swap_b32_e32 v24, v28
	v_permlane16_swap_b32_e32 v25, v29
	v_permlane16_swap_b32_e32 v26, v30
	v_permlane16_swap_b32_e32 v27, v31
	v_permlane16_swap_b32_e32 v16, v20
	v_permlane16_swap_b32_e32 v17, v21
	v_permlane16_swap_b32_e32 v18, v22
	v_permlane16_swap_b32_e32 v19, v23
	v_permlane16_swap_b32_e32 v8, v12
	v_permlane16_swap_b32_e32 v9, v13
	v_permlane16_swap_b32_e32 v10, v14
	v_permlane16_swap_b32_e32 v11, v15
	v_permlane16_swap_b32_e32 v4, v0
	v_permlane16_swap_b32_e32 v5, v1
	v_permlane16_swap_b32_e32 v6, v2
	v_permlane16_swap_b32_e32 v7, v3
	s_waitcnt vmcnt(14)
	v_pk_add_f32 v[126:127], v[198:199], v[126:127]
	v_pk_add_f32 v[122:123], v[202:203], v[122:123]
	v_pk_add_f32 v[120:121], v[200:201], v[120:121]
	v_pk_add_f32 v[124:125], v[196:197], v[124:125]
	global_store_dwordx4 v[128:129], v[120:123], off
	global_store_dwordx4 v[128:129], v[124:127], off offset:16
	global_load_dwordx4 v[196:199], v[128:129], off offset:528
	global_load_dwordx4 v[200:203], v[128:129], off offset:512
	s_waitcnt vmcnt(16)
	v_pk_add_f32 v[118:119], v[206:207], v[118:119]
	v_pk_add_f32 v[114:115], v[210:211], v[114:115]
	v_pk_add_f32 v[112:113], v[208:209], v[112:113]
	v_pk_add_f32 v[116:117], v[204:205], v[116:117]
	global_store_dwordx4 v[128:129], v[112:115], off offset:128
	global_store_dwordx4 v[128:129], v[116:119], off offset:144
	global_load_dwordx4 v[204:207], v[128:129], off offset:656
	global_load_dwordx4 v[208:211], v[128:129], off offset:640
	s_waitcnt vmcnt(18)
	v_pk_add_f32 v[110:111], v[214:215], v[110:111]
	v_pk_add_f32 v[106:107], v[218:219], v[106:107]
	v_pk_add_f32 v[104:105], v[216:217], v[104:105]
	v_pk_add_f32 v[108:109], v[212:213], v[108:109]
	global_store_dwordx4 v[244:245], v[104:107], off
	global_store_dwordx4 v[244:245], v[108:111], off offset:16
	global_load_dwordx4 v[212:215], v[244:245], off offset:528
	global_load_dwordx4 v[216:219], v[244:245], off offset:512
	s_waitcnt vmcnt(20)
	v_pk_add_f32 v[98:99], v[222:223], v[98:99]
	v_pk_add_f32 v[102:103], v[226:227], v[102:103]
	v_pk_add_f32 v[100:101], v[224:225], v[100:101]
	v_pk_add_f32 v[96:97], v[220:221], v[96:97]
	global_store_dwordx4 v[244:245], v[100:103], off offset:128
	global_store_dwordx4 v[244:245], v[96:99], off offset:144
	global_load_dwordx4 v[220:223], v[244:245], off offset:656
	global_load_dwordx4 v[224:227], v[244:245], off offset:640
	s_waitcnt vmcnt(22)
	v_pk_add_f32 v[94:95], v[230:231], v[94:95]
	v_pk_add_f32 v[90:91], v[234:235], v[90:91]
	v_pk_add_f32 v[88:89], v[232:233], v[88:89]
	v_pk_add_f32 v[92:93], v[228:229], v[92:93]
	global_store_dwordx4 v[246:247], v[88:91], off
	global_store_dwordx4 v[246:247], v[92:95], off offset:16
	global_load_dwordx4 v[228:231], v[246:247], off offset:528
	global_load_dwordx4 v[232:235], v[246:247], off offset:512
	s_waitcnt vmcnt(24)
; #define SCHEDB() __builtin_amdgcn_sched_barrier(0)
; DEVI void gemm_residual(const bfr* W, const bfr* X, int K, float* out, char* shm, const float* xp = nullptr, const float* xs = nullptr) {
;     ...
;             const int tk = pb * 256 + bj * 128 + e_wc * 32 + n * 16 + e_fr;
;             const int fi = pa * 256 + ai * 128 + e_wr * 64 + (m + (e_fq & 1)) * 16 + (e_fq >> 1) * 8;
;             f32x4* d = reinterpret_cast<f32x4*>(out + (long)tk * DM + fi);
;             const f32x4* sp = xp ? reinterpret_cast<const f32x4*>((tk < 16384 ? xp + (long)tk * DM : xs + (long)(tk - 16384) * DM) + fi) : d;
;             f32x4 o0 = sp[0], o1 = sp[1];
;             const f32x4 va = acc[ai][bj][m][n], vb2 = acc[ai][bj][m + 1][n];
; #pragma unroll
;             for (int e = 0; e < 4; ++e) { auto rr = __builtin_amdgcn_permlane16_swap(__float_as_uint(va[e]), __float_as_uint(vb2[e]), false, false);
;               o0[e] += __uint_as_float(rr[0]); o1[e] += __uint_as_float(rr[1]); }
;             d[0] = o0; d[1] = o1; }
;         SCHEDB(); } });
	v_pk_add_f32 v[86:87], v[238:239], v[86:87]
	v_pk_add_f32 v[82:83], v[242:243], v[82:83]
	v_pk_add_f32 v[80:81], v[240:241], v[80:81]
	v_pk_add_f32 v[84:85], v[236:237], v[84:85]
	global_store_dwordx4 v[246:247], v[80:83], off offset:128
	global_store_dwordx4 v[246:247], v[84:87], off offset:144
	global_load_dwordx4 v[236:239], v[246:247], off offset:656
	global_load_dwordx4 v[240:243], v[246:247], off offset:640
	s_waitcnt vmcnt(26)
	v_pk_add_f32 v[78:79], v[176:177], v[78:79]
	v_pk_add_f32 v[74:75], v[180:181], v[74:75]
	v_pk_add_f32 v[72:73], v[178:179], v[72:73]
	v_pk_add_f32 v[76:77], v[174:175], v[76:77]
	global_store_dwordx4 v[248:249], v[72:75], off
	global_store_dwordx4 v[248:249], v[76:79], off offset:16
	global_load_dwordx4 v[174:177], v[248:249], off offset:528
	global_load_dwordx4 v[178:181], v[248:249], off offset:512
	s_waitcnt vmcnt(28)
	v_pk_add_f32 v[66:67], v[184:185], v[66:67]
	v_pk_add_f32 v[70:71], v[188:189], v[70:71]
	v_pk_add_f32 v[68:69], v[186:187], v[68:69]
	v_pk_add_f32 v[64:65], v[182:183], v[64:65]
	global_store_dwordx4 v[248:249], v[68:71], off offset:128
	global_store_dwordx4 v[248:249], v[64:67], off offset:144
	global_load_dwordx4 v[182:185], v[248:249], off offset:656
	global_load_dwordx4 v[186:189], v[248:249], off offset:640
	s_waitcnt vmcnt(28)
	v_pk_add_f32 v[62:63], v[198:199], v[62:63]
	v_pk_add_f32 v[58:59], v[202:203], v[58:59]
	v_pk_add_f32 v[56:57], v[200:201], v[56:57]
	v_pk_add_f32 v[60:61], v[196:197], v[60:61]
	global_store_dwordx4 v[128:129], v[56:59], off offset:512
	global_store_dwordx4 v[128:129], v[60:63], off offset:528
	s_waitcnt vmcnt(26)
	v_pk_add_f32 v[54:55], v[206:207], v[54:55]
	v_pk_add_f32 v[50:51], v[210:211], v[50:51]
	v_pk_add_f32 v[48:49], v[208:209], v[48:49]
	v_pk_add_f32 v[52:53], v[204:205], v[52:53]
	global_store_dwordx4 v[128:129], v[48:51], off offset:640
	global_store_dwordx4 v[128:129], v[52:55], off offset:656
	s_waitcnt vmcnt(24)
	v_pk_add_f32 v[46:47], v[214:215], v[46:47]
	v_pk_add_f32 v[42:43], v[218:219], v[42:43]
	v_pk_add_f32 v[40:41], v[216:217], v[40:41]
	v_pk_add_f32 v[44:45], v[212:213], v[44:45]
	global_store_dwordx4 v[244:245], v[40:43], off offset:512
	global_store_dwordx4 v[244:245], v[44:47], off offset:528
	s_waitcnt vmcnt(22)
	v_pk_add_f32 v[34:35], v[222:223], v[34:35]
	v_pk_add_f32 v[38:39], v[226:227], v[38:39]
	v_pk_add_f32 v[36:37], v[224:225], v[36:37]
	v_pk_add_f32 v[32:33], v[220:221], v[32:33]
	global_store_dwordx4 v[244:245], v[36:39], off offset:640
	global_store_dwordx4 v[244:245], v[32:35], off offset:656
	s_waitcnt vmcnt(20)
	v_pk_add_f32 v[30:31], v[230:231], v[30:31]
	v_pk_add_f32 v[26:27], v[234:235], v[26:27]
	v_pk_add_f32 v[24:25], v[232:233], v[24:25]
	v_pk_add_f32 v[28:29], v[228:229], v[28:29]
	global_store_dwordx4 v[246:247], v[24:27], off offset:512
	global_store_dwordx4 v[246:247], v[28:31], off offset:528
	s_waitcnt vmcnt(18)
	v_pk_add_f32 v[22:23], v[238:239], v[22:23]
	v_pk_add_f32 v[18:19], v[242:243], v[18:19]
	v_pk_add_f32 v[16:17], v[240:241], v[16:17]
	v_pk_add_f32 v[20:21], v[236:237], v[20:21]
	global_store_dwordx4 v[246:247], v[16:19], off offset:640
	global_store_dwordx4 v[246:247], v[20:23], off offset:656
	s_waitcnt vmcnt(16)
	v_pk_add_f32 v[14:15], v[176:177], v[14:15]
	v_pk_add_f32 v[10:11], v[180:181], v[10:11]
	v_pk_add_f32 v[8:9], v[178:179], v[8:9]
	v_pk_add_f32 v[12:13], v[174:175], v[12:13]
	global_store_dwordx4 v[248:249], v[8:11], off offset:512
	global_store_dwordx4 v[248:249], v[12:15], off offset:528
	s_waitcnt vmcnt(14)
	v_pk_add_f32 v[2:3], v[184:185], v[2:3]
	v_pk_add_f32 v[6:7], v[188:189], v[6:7]
	v_pk_add_f32 v[4:5], v[186:187], v[4:5]
	v_pk_add_f32 v[0:1], v[182:183], v[0:1]
	global_store_dwordx4 v[248:249], v[4:7], off offset:640
	global_store_dwordx4 v[248:249], v[0:3], off offset:656
	s_and_b64 vcc, exec, s[8:9]
	s_mov_b32 s11, s72
	s_mov_b32 s2, s69
	s_cbranch_vccnz .LBB0_387

; DEVI int nblk() { int n = NBLK; asm volatile("" : "+s"(n)); return n; }
; DEVI void tile_decode(int t, int ntiles, int ntA, int& pa, int& pb) {
;     ...
;   int grp = tp / (16 * ntA), rem = tp % (16 * ntA); pa = rem >> 4; pb = grp * 16 + (rem & 15);
; template <class EPI>
; DEVI void gemm8_linear(const bfr* A, int ntA, const bfr* B, int ntB, int K, char* shm, EPI epi) {
;     ...
;     const int tn = t + nblk(); int pan = 0, pbn = 0; const bool hn = tn < ntiles;
;     if (hn) tile_decode(tn, ntiles, ntA, pan, pbn);
.LBB0_378:
	s_ashr_i32 s0, s1, 31
	s_lshr_b32 s0, s0, 25
	s_add_i32 s0, s1, s0
	s_ashr_i32 s10, s0, 7
	s_and_b32 s0, s0, 0xffffff80
	s_sub_i32 s0, s1, s0
	s_ashr_i32 s69, s0, 4
	s_lshl_b32 s1, s10, 4
	s_and_b32 s0, s0, 15
	s_or_b32 s72, s0, s1
	s_sub_i32 s72, 0x7f, s72

; DEVI unsigned cvtpk(float lo, float hi) { unsigned r; asm volatile("v_cvt_pk_bf16_f32 %0, %1, %2" : "=v"(r) : "v"(lo), "v"(hi)); return r; }
; DEVI int nblk() { int n = NBLK; asm volatile("" : "+s"(n)); return n; }
; DEVI int obid() { int b = blockIdx.x; asm volatile("" : "+s"(b)); return b; }
; DEVI void phase_rmsnorm(const float* __restrict__ x, const float* __restrict__ g, bfr* __restrict__ h, const float* __restrict__ xp = nullptr, const float* __restrict__ xs = nullptr) {
;     ...
;   for (int t = obid() * 8 + wid; t < T; t += nblk() * 8) {
;     const f32x4* xr = (const f32x4*)(xp ? (t < 16384 ? xp + (long)t * DM : xs + (long)(t - 16384) * DM) : x + (long)t * DM);
;     f32x4 v[8]; float ss = 0;
; #pragma unroll
;     for (int i = 0; i < 4; ++i) { v[2 * i] = xr[i * 128 + lane * 2]; v[2 * i + 1] = xr[i * 128 + lane * 2 + 1]; }
; #pragma unroll
;     for (int i = 0; i < 8; ++i) ss += v[i][0] * v[i][0] + v[i][1] * v[i][1] + v[i][2] * v[i][2] + v[i][3] * v[i][3];
;     ss = wave_sum(ss);
;     const float r = rsqrtf(ss * (1.f / DM) + EPS);
; #pragma unroll
;     for (int i = 0; i < 4; ++i) { const f32x4 g0 = ((const f32x4*)g)[i * 128 + lane * 2], g1 = ((const f32x4*)g)[i * 128 + lane * 2 + 1];
;       const f32x4 a = v[2 * i], c = v[2 * i + 1];
;       u32x4 w = {cvtpk(a[0] * r * g0[0], a[1] * r * g0[1]), cvtpk(a[2] * r * g0[2], a[3] * r * g0[3]),
;                  cvtpk(c[0] * r * g1[0], c[1] * r * g1[1]), cvtpk(c[2] * r * g1[2], c[3] * r * g1[3])};
;       *reinterpret_cast<u32x4*>(h + (long)t * DM + i * 512 + lane * 8) = w; }
.LBB0_411:
	v_sub_u32_e32 v232, 0x7fff, v40
	v_mov_b32_e32 v233, 0
	v_lshlrev_b64 v[8:9], 13, v[232:233]
	v_lshl_add_u64 v[8:9], s[10:11], 0, v[8:9]
	v_lshl_add_u64 v[10:11], v[8:9], 0, v[166:167]
	global_load_dwordx4 v[32:35], v[10:11], off offset:16
	global_load_dwordx4 v[36:39], v[10:11], off
	global_load_dwordx4 v[24:27], v[10:11], off offset:2064
	global_load_dwordx4 v[28:31], v[10:11], off offset:2048
	v_mov_b32_e32 v51, v167
	v_lshl_add_u64 v[10:11], v[8:9], 0, v[50:51]
	global_load_dwordx4 v[20:23], v[10:11], off
	global_load_dwordx4 v[16:19], v[10:11], off offset:16
	v_mov_b32_e32 v53, v167
	v_lshl_add_u64 v[8:9], v[8:9], 0, v[52:53]
	global_load_dwordx4 v[12:15], v[8:9], off
	s_nop 0
	global_load_dwordx4 v[8:11], v[8:9], off offset:16
	s_movk_i32 s2, 0x100
	s_waitcnt vmcnt(0)
	v_mul_f32_e32 v53, v33, v33
	v_mul_f32_e32 v51, v37, v37
	v_fmac_f32_e32 v51, v36, v36
	v_fmac_f32_e32 v53, v32, v32
	v_fmac_f32_e32 v51, v38, v38
	v_fmac_f32_e32 v53, v34, v34
	v_fmac_f32_e32 v51, v39, v39
	v_fmac_f32_e32 v53, v35, v35
	v_add_f32_e32 v51, v51, v53
	v_mul_f32_e32 v53, v29, v29
	v_fmac_f32_e32 v53, v28, v28
	v_fmac_f32_e32 v53, v30, v30
	v_fmac_f32_e32 v53, v31, v31
	v_add_f32_e32 v51, v51, v53
	v_mul_f32_e32 v53, v25, v25
	v_mov_b32_e32 v62, v21
	v_mov_b32_e32 v63, v17
	v_fmac_f32_e32 v53, v24, v24
	v_mov_b32_e32 v54, v20
	v_mov_b32_e32 v55, v16
	v_pk_mul_f32 v[62:63], v[62:63], v[62:63]
	v_fmac_f32_e32 v53, v26, v26
	v_pk_fma_f32 v[54:55], v[54:55], v[54:55], v[62:63]
	v_mov_b32_e32 v62, v22
	v_mov_b32_e32 v63, v18
	v_fmac_f32_e32 v53, v27, v27
	v_pk_fma_f32 v[54:55], v[62:63], v[62:63], v[54:55]
	v_mov_b32_e32 v62, v23
	v_mov_b32_e32 v63, v19
	v_add_f32_e32 v51, v51, v53
	v_pk_fma_f32 v[54:55], v[62:63], v[62:63], v[54:55]
	v_mov_b32_e32 v62, v13
	v_add_f32_e32 v51, v51, v54
	v_mov_b32_e32 v63, v9
	v_add_f32_e32 v51, v51, v55
	v_mov_b32_e32 v54, v12
	v_mov_b32_e32 v55, v8
	v_pk_mul_f32 v[62:63], v[62:63], v[62:63]
	s_nop 0
	v_pk_fma_f32 v[54:55], v[54:55], v[54:55], v[62:63]
	v_mov_b32_e32 v62, v14
	v_mov_b32_e32 v63, v10
	v_pk_fma_f32 v[54:55], v[62:63], v[62:63], v[54:55]
	v_mov_b32_e32 v62, v15
	v_mov_b32_e32 v63, v11
	v_pk_fma_f32 v[54:55], v[62:63], v[62:63], v[54:55]
	s_nop 0
	v_add_f32_e32 v51, v51, v54
	v_add_f32_e32 v51, v51, v55
	ds_bpermute_b32 v53, v56, v51
	v_lshlrev_b64 v[54:55], 12, v[232:233]
	v_lshl_add_u64 v[54:55], v[42:43], 0, v[54:55]
	s_waitcnt lgkmcnt(0)
	v_add_f32_e32 v51, v51, v53
	ds_bpermute_b32 v53, v57, v51
	s_waitcnt lgkmcnt(0)
	v_add_f32_e32 v51, v51, v53
	ds_bpermute_b32 v53, v58, v51
	s_waitcnt lgkmcnt(0)
	v_add_f32_e32 v51, v51, v53
	ds_bpermute_b32 v53, v59, v51
	s_waitcnt lgkmcnt(0)
	v_add_f32_e32 v51, v51, v53
	ds_bpermute_b32 v53, v60, v51
	s_waitcnt lgkmcnt(0)
	v_add_f32_e32 v51, v51, v53
	ds_bpermute_b32 v53, v61, v51
	s_waitcnt lgkmcnt(0)
	v_add_f32_e32 v51, v51, v53
	v_fmamk_f32 v51, v51, 0x3a000000, v168
	v_cmp_gt_f32_e32 vcc, s6, v51
	v_mul_f32_e32 v53, 0x4b800000, v51
	s_nop 0
	v_cndmask_b32_e32 v51, v51, v53, vcc
	v_rsq_f32_e32 v51, v51
	s_nop 0
	v_mul_f32_e32 v53, 0x45800000, v51
	v_cndmask_b32_e32 v51, v51, v53, vcc
	v_mul_f32_e32 v36, v36, v51
	v_mul_f32_e32 v37, v37, v51
	v_mul_f32_e32 v36, v0, v36
	v_mul_f32_e32 v37, v1, v37
	v_cvt_pk_bf16_f32 v36, v36, v37
	v_mul_f32_e32 v37, v38, v51
	v_mul_f32_e32 v38, v39, v51
	v_mul_f32_e32 v32, v32, v51
	v_mul_f32_e32 v33, v33, v51
	v_mul_f32_e32 v37, v2, v37
	v_mul_f32_e32 v38, v3, v38
	v_mul_f32_e32 v32, v4, v32
	v_mul_f32_e32 v33, v5, v33
	v_cvt_pk_bf16_f32 v37, v37, v38
	v_cvt_pk_bf16_f32 v38, v32, v33
	v_mul_f32_e32 v32, v34, v51
	v_mul_f32_e32 v33, v35, v51
	v_mul_f32_e32 v32, v6, v32
	v_mul_f32_e32 v33, v7, v33
	v_cvt_pk_bf16_f32 v39, v32, v33
	global_store_dwordx4 v[54:55], v[36:39], off
	v_mul_f32_e32 v28, v28, v51
	v_mul_f32_e32 v29, v29, v51
	v_mul_f32_e32 v24, v24, v51
	v_mul_f32_e32 v25, v25, v51
	v_mul_f32_e32 v20, v20, v51
	v_mul_f32_e32 v21, v21, v51
	v_mul_f32_e32 v16, v16, v51
	v_mul_f32_e32 v17, v17, v51
	v_mul_f32_e32 v12, v12, v51
	v_mul_f32_e32 v13, v13, v51
	v_mul_f32_e32 v8, v8, v51
	v_mul_f32_e32 v9, v9, v51
	v_mul_f32_e32 v24, v212, v24
	v_mul_f32_e32 v28, v208, v28
	v_mul_f32_e32 v29, v209, v29
	v_cvt_pk_bf16_f32 v28, v28, v29
	v_mul_f32_e32 v29, v30, v51
	v_mul_f32_e32 v30, v31, v51
	v_mul_f32_e32 v29, v210, v29
	v_mul_f32_e32 v30, v211, v30
	v_mul_f32_e32 v25, v213, v25
	v_cvt_pk_bf16_f32 v29, v29, v30
	v_cvt_pk_bf16_f32 v30, v24, v25
	v_mul_f32_e32 v24, v26, v51
	v_mul_f32_e32 v25, v27, v51
	v_mul_f32_e32 v24, v214, v24
	v_mul_f32_e32 v25, v215, v25
	v_cvt_pk_bf16_f32 v31, v24, v25
	global_store_dwordx4 v[54:55], v[28:31], off offset:1024
	v_mul_f32_e32 v16, v16, v220
	v_mul_f32_e32 v20, v20, v216
	v_mul_f32_e32 v21, v21, v217
	v_cvt_pk_bf16_f32 v20, v20, v21
	v_mul_f32_e32 v21, v22, v51
	v_mul_f32_e32 v22, v23, v51
	v_mul_f32_e32 v21, v21, v218
	v_mul_f32_e32 v22, v22, v219
	v_mul_f32_e32 v17, v17, v221
	v_cvt_pk_bf16_f32 v21, v21, v22
	v_cvt_pk_bf16_f32 v22, v16, v17
	v_mul_f32_e32 v16, v18, v51
	v_mul_f32_e32 v17, v19, v51
	v_mul_f32_e32 v16, v16, v222
	v_mul_f32_e32 v17, v17, v223
	v_cvt_pk_bf16_f32 v23, v16, v17
	global_store_dwordx4 v[54:55], v[20:23], off offset:2048
	v_mul_f32_e32 v8, v8, v228
	v_mul_f32_e32 v12, v12, v224
	v_mul_f32_e32 v13, v13, v225
	v_cvt_pk_bf16_f32 v12, v12, v13
	v_mul_f32_e32 v13, v14, v51
	v_mul_f32_e32 v14, v15, v51
	v_mul_f32_e32 v13, v13, v226
	v_mul_f32_e32 v14, v14, v227
	v_mul_f32_e32 v9, v9, v229
	v_cvt_pk_bf16_f32 v13, v13, v14
	v_cvt_pk_bf16_f32 v14, v8, v9
	v_mul_f32_e32 v8, v10, v51
	v_mul_f32_e32 v9, v11, v51
	v_mul_f32_e32 v8, v8, v230
	v_mul_f32_e32 v9, v9, v231
	v_cvt_pk_bf16_f32 v15, v8, v9
	global_store_dwordx4 v[54:55], v[12:15], off offset:3072
	s_nop 0
	v_lshl_add_u32 v40, s2, 3, v40
	v_cmp_lt_i32_e32 vcc, s7, v40
	s_or_b64 s[4:5], vcc, s[4:5]
	s_andn2_b64 exec, exec, s[4:5]
	s_cbranch_execnz .LBB0_411
